# P2 epilogue stores write-back (no sc1) so next tile's vmcnt does not wait for write-through drain; + swapped-V, nop drop, preamble burst
# speedup vs baseline: 1.0033x; 1.0033x over previous
; __device__ __forceinline__ unsigned pk2(float lo, float hi) { return pg8::cvt_pk_bf16(lo, hi); }
;     __device__ __forceinline__ void operator()(const f32x4 (&acc)[2][2][4][2], const pg8::Unit& u, int wr, int wc, int fr, int fq) const {
;     ...
;         } else {
; #pragma unroll
;             for (int ai = 0; ai < 2; ++ai)
; #pragma unroll
;                 for (int m = 0; m < 4; ++m) { const unsigned row = (unsigned)(row0 + ai * 128 + m * 16);
; #pragma unroll
;                     for (int bj = 0; bj < 2; ++bj) { const f32x4 v0 = acc[ai][bj][m][0], v1 = acc[ai][bj][m][1];
;                         u32x4 w; w.x = pk2(v0.x, v0.y); w.y = pk2(v0.z, v0.w); w.z = pk2(v1.x, v1.y); w.w = pk2(v1.z, v1.w);
;                         st16wt(BG, (row * 512 + 256 * (pn - 10) + 128 * bj + 32 * wc + 8 * fq) * 2u, w); } }
.LBB0_280:
	s_cmp_gt_u32 s21, 5
	s_cbranch_scc0 .LBB0_286
	s_cmp_lt_u32 s21, 10
	s_cbranch_scc1 .LBB0_283
	s_lshl_b32 s0, s21, 9
	s_addk_i32 s0, 0xec00
	v_lshl_add_u32 v136, v146, 10, s0
	v_cvt_pk_bf16_f32 v148, v124, v125
	v_cvt_pk_bf16_f32 v149, v126, v127
	v_cvt_pk_bf16_f32 v150, v120, v121
	v_cvt_pk_bf16_f32 v151, v122, v123
	v_or_b32_e32 v147, v136, v159
	buffer_store_dwordx4 v[148:151], v147, s[16:19], 0 offen
	s_mov_b64 s[14:15], 0
	s_nop 0
	v_cvt_pk_bf16_f32 v148, v116, v117
	v_cvt_pk_bf16_f32 v149, v118, v119
	v_cvt_pk_bf16_f32 v150, v108, v109
	v_cvt_pk_bf16_f32 v151, v110, v111
	buffer_store_dwordx4 v[148:151], v147, s[16:19], 0 offen offset:256
	v_add_u32_e32 v147, v136, v160
	s_nop 0
	v_cvt_pk_bf16_f32 v148, v112, v113
	v_cvt_pk_bf16_f32 v149, v114, v115
	v_cvt_pk_bf16_f32 v150, v104, v105
	v_cvt_pk_bf16_f32 v151, v106, v107
	buffer_store_dwordx4 v[148:151], v147, s[16:19], 0 offen
	s_nop 1
	v_cvt_pk_bf16_f32 v148, v100, v101
	v_cvt_pk_bf16_f32 v149, v102, v103
	v_cvt_pk_bf16_f32 v150, v92, v93
	v_cvt_pk_bf16_f32 v151, v94, v95
	buffer_store_dwordx4 v[148:151], v147, s[16:19], 0 offen offset:256
	v_add_u32_e32 v147, v136, v161
	s_nop 0
	v_cvt_pk_bf16_f32 v148, v96, v97
	v_cvt_pk_bf16_f32 v149, v98, v99
	v_cvt_pk_bf16_f32 v150, v88, v89
	v_cvt_pk_bf16_f32 v151, v90, v91
	buffer_store_dwordx4 v[148:151], v147, s[16:19], 0 offen
	s_nop 1
	v_cvt_pk_bf16_f32 v148, v84, v85
	v_cvt_pk_bf16_f32 v149, v86, v87
	v_cvt_pk_bf16_f32 v150, v76, v77
	v_cvt_pk_bf16_f32 v151, v78, v79
	buffer_store_dwordx4 v[148:151], v147, s[16:19], 0 offen offset:256
	v_add_u32_e32 v147, v136, v162
	s_nop 0
	v_cvt_pk_bf16_f32 v148, v80, v81
	v_cvt_pk_bf16_f32 v149, v82, v83
	v_cvt_pk_bf16_f32 v150, v72, v73
	v_cvt_pk_bf16_f32 v151, v74, v75
	buffer_store_dwordx4 v[148:151], v147, s[16:19], 0 offen
	s_nop 1
	v_cvt_pk_bf16_f32 v148, v68, v69
	v_cvt_pk_bf16_f32 v149, v70, v71
	v_cvt_pk_bf16_f32 v150, v64, v65
	v_cvt_pk_bf16_f32 v151, v66, v67
	buffer_store_dwordx4 v[148:151], v147, s[16:19], 0 offen offset:256
	v_add_u32_e32 v147, v136, v163
	s_nop 0
	v_cvt_pk_bf16_f32 v148, v60, v61
	v_cvt_pk_bf16_f32 v149, v62, v63
	v_cvt_pk_bf16_f32 v150, v56, v57
	v_cvt_pk_bf16_f32 v151, v58, v59
	buffer_store_dwordx4 v[148:151], v147, s[16:19], 0 offen
	s_nop 1
	v_cvt_pk_bf16_f32 v148, v52, v53
	v_cvt_pk_bf16_f32 v149, v54, v55
	v_cvt_pk_bf16_f32 v150, v44, v45
	v_cvt_pk_bf16_f32 v151, v46, v47
	buffer_store_dwordx4 v[148:151], v147, s[16:19], 0 offen offset:256
	v_add_u32_e32 v147, v136, v164
	s_nop 0
	v_cvt_pk_bf16_f32 v148, v48, v49
	v_cvt_pk_bf16_f32 v149, v50, v51
	v_cvt_pk_bf16_f32 v150, v40, v41
	v_cvt_pk_bf16_f32 v151, v42, v43
	buffer_store_dwordx4 v[148:151], v147, s[16:19], 0 offen
	s_nop 1
	v_cvt_pk_bf16_f32 v148, v36, v37
	v_cvt_pk_bf16_f32 v149, v38, v39
	v_cvt_pk_bf16_f32 v150, v28, v29
	v_cvt_pk_bf16_f32 v151, v30, v31
	buffer_store_dwordx4 v[148:151], v147, s[16:19], 0 offen offset:256
	v_add_u32_e32 v147, v136, v165
	v_add_u32_e32 v136, v136, v166
	v_cvt_pk_bf16_f32 v148, v32, v33
	v_cvt_pk_bf16_f32 v149, v34, v35
	v_cvt_pk_bf16_f32 v150, v24, v25
	v_cvt_pk_bf16_f32 v151, v26, v27
	buffer_store_dwordx4 v[148:151], v147, s[16:19], 0 offen
	s_nop 1
	v_cvt_pk_bf16_f32 v148, v20, v21
	v_cvt_pk_bf16_f32 v149, v22, v23
	v_cvt_pk_bf16_f32 v150, v12, v13
	v_cvt_pk_bf16_f32 v151, v14, v15
	buffer_store_dwordx4 v[148:151], v147, s[16:19], 0 offen offset:256
	s_nop 1
	v_cvt_pk_bf16_f32 v148, v16, v17
	v_cvt_pk_bf16_f32 v149, v18, v19
	v_cvt_pk_bf16_f32 v150, v8, v9
	v_cvt_pk_bf16_f32 v151, v10, v11
	buffer_store_dwordx4 v[148:151], v136, s[16:19], 0 offen
	s_nop 1
	v_cvt_pk_bf16_f32 v148, v4, v5
	v_cvt_pk_bf16_f32 v149, v6, v7
	v_cvt_pk_bf16_f32 v150, v0, v1
	v_cvt_pk_bf16_f32 v151, v2, v3
	buffer_store_dwordx4 v[148:151], v136, s[16:19], 0 offen offset:256
; __device__ __forceinline__ unsigned pk2(float lo, float hi) { return pg8::cvt_pk_bf16(lo, hi); }
;     __device__ __forceinline__ void operator()(const f32x4 (&acc)[2][2][4][2], const pg8::Unit& u, int wr, int wc, int fr, int fq) const {
;     ...
;         } else if (pn < 10) {
;             const int ch0 = 128 * (pn - 6) + 32 * wc + 8 * fq;
; #pragma unroll
;             for (int ai = 0; ai < 2; ++ai)
; #pragma unroll
;                 for (int m = 0; m < 4; ++m) { const unsigned row = (unsigned)(row0 + ai * 128 + m * 16);
;                     const f32x4 v0 = acc[ai][0][m][0] * acc[ai][1][m][0], v1 = acc[ai][0][m][1] * acc[ai][1][m][1];
;                     u32x4 w; w.x = pk2(v0.x, v0.y); w.y = pk2(v0.z, v0.w); w.z = pk2(v1.x, v1.y); w.w = pk2(v1.z, v1.w);
;                     st16wt(Z, (row * 512 + ch0) * 2u, w); }
.LBB0_283:
	s_andn2_b64 vcc, exec, s[14:15]
	s_cbranch_vccnz .LBB0_285
	v_pk_mul_f32 v[150:151], v[126:127], v[118:119]
	v_pk_mul_f32 v[148:149], v[124:125], v[116:117]
	v_lshlrev_b32_e32 v136, 10, v146
	s_lshl_b32 s0, s21, 8
	v_pk_mul_f32 v[152:153], v[122:123], v[110:111]
	v_pk_mul_f32 v[178:179], v[120:121], v[108:109]
	v_cvt_pk_bf16_f32 v148, v148, v149
	v_cvt_pk_bf16_f32 v149, v150, v151
	v_add3_u32 v136, v168, s0, v136
	v_cvt_pk_bf16_f32 v150, v178, v179
	v_cvt_pk_bf16_f32 v151, v152, v153
	s_mov_b32 s14, s18
	s_mov_b32 s15, s19
	buffer_store_dwordx4 v[148:151], v136, s[12:15], 0 offen
	v_pk_mul_f32 v[152:153], v[106:107], v[94:95]
	v_pk_mul_f32 v[178:179], v[104:105], v[92:93]
	v_pk_mul_f32 v[150:151], v[114:115], v[102:103]
	v_pk_mul_f32 v[148:149], v[112:113], v[100:101]
	v_add_u32_e32 v147, 0x4000, v136
	v_cvt_pk_bf16_f32 v148, v148, v149
	v_cvt_pk_bf16_f32 v149, v150, v151
	v_cvt_pk_bf16_f32 v150, v178, v179
	v_cvt_pk_bf16_f32 v151, v152, v153
	buffer_store_dwordx4 v[148:151], v147, s[12:15], 0 offen
	v_pk_mul_f32 v[152:153], v[90:91], v[78:79]
	v_pk_mul_f32 v[178:179], v[88:89], v[76:77]
	v_pk_mul_f32 v[150:151], v[98:99], v[86:87]
	v_pk_mul_f32 v[148:149], v[96:97], v[84:85]
	v_add_u32_e32 v147, 0x8000, v136
	v_cvt_pk_bf16_f32 v148, v148, v149
	v_cvt_pk_bf16_f32 v149, v150, v151
	v_cvt_pk_bf16_f32 v150, v178, v179
	v_cvt_pk_bf16_f32 v151, v152, v153
	buffer_store_dwordx4 v[148:151], v147, s[12:15], 0 offen
	v_pk_mul_f32 v[152:153], v[74:75], v[66:67]
	v_pk_mul_f32 v[178:179], v[72:73], v[64:65]
	v_pk_mul_f32 v[150:151], v[82:83], v[70:71]
	v_pk_mul_f32 v[148:149], v[80:81], v[68:69]
	v_add_u32_e32 v147, 0xc000, v136
	v_cvt_pk_bf16_f32 v148, v148, v149
	v_cvt_pk_bf16_f32 v149, v150, v151
	v_cvt_pk_bf16_f32 v150, v178, v179
	v_cvt_pk_bf16_f32 v151, v152, v153
	buffer_store_dwordx4 v[148:151], v147, s[12:15], 0 offen
	v_pk_mul_f32 v[152:153], v[58:59], v[46:47]
	v_pk_mul_f32 v[178:179], v[56:57], v[44:45]
	v_pk_mul_f32 v[150:151], v[62:63], v[54:55]
	v_pk_mul_f32 v[148:149], v[60:61], v[52:53]
	v_add_u32_e32 v147, 0x20000, v136
	v_cvt_pk_bf16_f32 v148, v148, v149
	v_cvt_pk_bf16_f32 v149, v150, v151
	v_cvt_pk_bf16_f32 v150, v178, v179
	v_cvt_pk_bf16_f32 v151, v152, v153
	buffer_store_dwordx4 v[148:151], v147, s[12:15], 0 offen
	v_pk_mul_f32 v[152:153], v[42:43], v[30:31]
	v_pk_mul_f32 v[178:179], v[40:41], v[28:29]
	v_pk_mul_f32 v[150:151], v[50:51], v[38:39]
	v_pk_mul_f32 v[148:149], v[48:49], v[36:37]
	v_add_u32_e32 v147, 0x24000, v136
	v_cvt_pk_bf16_f32 v148, v148, v149
	v_cvt_pk_bf16_f32 v149, v150, v151
	v_cvt_pk_bf16_f32 v150, v178, v179
	v_cvt_pk_bf16_f32 v151, v152, v153
	buffer_store_dwordx4 v[148:151], v147, s[12:15], 0 offen
	v_pk_mul_f32 v[152:153], v[26:27], v[14:15]
	v_pk_mul_f32 v[178:179], v[24:25], v[12:13]
	v_pk_mul_f32 v[150:151], v[34:35], v[22:23]
	v_pk_mul_f32 v[148:149], v[32:33], v[20:21]
	v_add_u32_e32 v147, 0x28000, v136
	v_cvt_pk_bf16_f32 v148, v148, v149
	v_cvt_pk_bf16_f32 v149, v150, v151
	v_cvt_pk_bf16_f32 v150, v178, v179
	v_cvt_pk_bf16_f32 v151, v152, v153
	buffer_store_dwordx4 v[148:151], v147, s[12:15], 0 offen
	v_add_u32_e32 v136, 0x2c000, v136
	v_pk_mul_f32 v[152:153], v[10:11], v[2:3]
	v_pk_mul_f32 v[150:151], v[18:19], v[6:7]
	v_pk_mul_f32 v[148:149], v[16:17], v[4:5]
	v_pk_mul_f32 v[178:179], v[8:9], v[0:1]
	v_cvt_pk_bf16_f32 v148, v148, v149
	v_cvt_pk_bf16_f32 v149, v150, v151
	s_nop 0
	v_cvt_pk_bf16_f32 v150, v178, v179
	v_cvt_pk_bf16_f32 v151, v152, v153
	buffer_store_dwordx4 v[148:151], v136, s[12:15], 0 offen

; __device__ __forceinline__ unsigned pk2(float lo, float hi) { return pg8::cvt_pk_bf16(lo, hi); }
;     __device__ __forceinline__ void operator()(const f32x4 (&acc)[2][2][4][2], const pg8::Unit& u, int wr, int wc, int fr, int fq) const {
;     ...
;         if (pn < 4) {
;             const bool isq = pn < 2; const float* g = isq ? qg : kg; bf16_t* dst = isq ? Q : K; const int head = 4 * (pn & 1) + wc; const float mul = isq ? C2 : 1.f;
;             f32x4 gv[2][2];
; #pragma unroll
;             for (int bj = 0; bj < 2; ++bj)
; #pragma unroll
;                 for (int n = 0; n < 2; ++n) gv[bj][n] = *(const f32x4*)(g + 32 * bj + 8 * fq + 4 * n) * mul;
; #pragma unroll
;             for (int ai = 0; ai < 2; ++ai)
; #pragma unroll
;                 for (int m = 0; m < 4; ++m) {
;                     float ss = 0.f;
; #pragma unroll
;                     for (int bj = 0; bj < 2; ++bj)
; #pragma unroll
;                         for (int n = 0; n < 2; ++n) { const f32x4 a = acc[ai][bj][m][n]; ss += (a.x * a.x + a.y * a.y) + (a.z * a.z + a.w * a.w); }
;                     ss += __shfl_xor(ss, 16); ss += __shfl_xor(ss, 32);
;                     const float rinv = rsqrtf(ss * (1.f / 64.f) + EPS);
;                     const unsigned row = (unsigned)(row0 + ai * 128 + m * 16);
; #pragma unroll
;                     for (int bj = 0; bj < 2; ++bj) { const f32x4 v0 = acc[ai][bj][m][0] * rinv * gv[bj][0], v1 = acc[ai][bj][m][1] * rinv * gv[bj][1];
;                         u32x4 w; w.x = pk2(v0.x, v0.y); w.y = pk2(v0.z, v0.w); w.z = pk2(v1.x, v1.y); w.w = pk2(v1.z, v1.w);
;                         st16wt(dst, (row * 512 + head * 64 + 32 * bj + 8 * fq) * 2u, w); }
;                 }
.LBB0_289:
	s_cmp_lt_i32 s21, 2
	s_cselect_b64 vcc, -1, 0
	s_and_b64 s[14:15], vcc, exec
	s_cselect_b32 s15, s31, s35
	s_cselect_b32 s14, s30, s34
	global_load_dwordx4 v[148:151], v172, s[14:15]
	global_load_dwordx4 v[180:183], v172, s[14:15] offset:16
	global_load_dwordx4 v[184:187], v172, s[14:15] offset:128
	global_load_dwordx4 v[188:191], v172, s[14:15] offset:144
	v_lshlrev_b32_e32 v201, 10, v146
	v_pk_mul_f32 v[146:147], v[126:127], v[126:127]
	v_pk_mul_f32 v[152:153], v[124:125], v[124:125]
	v_pk_mul_f32 v[178:179], v[122:123], v[122:123]
	v_pk_mul_f32 v[194:195], v[120:121], v[120:121]
	v_pk_mov_b32 v[198:199], v[152:153], v[146:147] op_sel:[1,0]
	v_mov_b32_e32 v153, v147
	v_pk_mov_b32 v[146:147], v[194:195], v[178:179] op_sel:[1,0]
	v_mov_b32_e32 v195, v179
	v_mul_f32_e32 v136, v117, v117
	v_mul_f32_e32 v196, v119, v119
	v_pk_add_f32 v[152:153], v[198:199], v[152:153]
	v_pk_add_f32 v[146:147], v[146:147], v[194:195]
	v_and_b32_e32 v193, 64, v176
	v_mul_f32_e32 v202, v108, v108
	v_mul_f32_e32 v203, v109, v109
	v_mul_f32_e32 v204, v110, v110
	v_mul_f32_e32 v205, v111, v111
	v_pk_fma_f32 v[178:179], v[116:117], v[116:117], v[136:137] op_sel_hi:[1,1,0]
	v_pk_fma_f32 v[196:197], v[118:119], v[118:119], v[196:197] op_sel_hi:[1,1,0]
	v_pk_add_f32 v[152:153], v[152:153], v[152:153] op_sel:[0,1] op_sel_hi:[1,0]
	v_pk_add_f32 v[146:147], v[146:147], v[146:147] op_sel:[0,1] op_sel_hi:[1,0]
	v_xor_b32_e32 v177, 16, v176
	v_add_u32_e32 v193, 64, v193
	v_mov_b32_e32 v179, v204
	v_mov_b32_e32 v197, v205
	v_mov_b32_e32 v153, v202
	v_mov_b32_e32 v147, v203
	v_cndmask_b32_e32 v192, 1.0, v175, vcc
	v_cmp_lt_i32_e32 vcc, v177, v193
	v_pk_add_f32 v[178:179], v[178:179], v[196:197]
	v_pk_add_f32 v[146:147], v[152:153], v[146:147]
	v_cndmask_b32_e32 v136, v176, v177, vcc
	v_pk_add_f32 v[146:147], v[146:147], v[178:179]
	v_lshlrev_b32_e32 v136, 2, v136
	v_add_f32_e32 v146, v146, v147
	ds_bpermute_b32 v147, v136, v146
	v_xor_b32_e32 v200, 32, v176
	v_cmp_lt_i32_e32 vcc, v200, v193
	s_cselect_b32 s0, s87, 0x5000000
	s_add_u32 s20, s36, s0
	v_cndmask_b32_e32 v152, v176, v200, vcc
	v_lshlrev_b32_e32 v177, 2, v152
	s_waitcnt lgkmcnt(0)
	v_add_f32_e32 v146, v146, v147
	ds_bpermute_b32 v147, v177, v146
	s_addc_u32 s0, s37, 0
	s_lshl_b32 s1, s21, 2
	s_and_b32 s1, s1, 4
	s_and_b32 s21, s0, 0xffff
	s_waitcnt lgkmcnt(0)
	v_add_f32_e32 v146, v146, v147
	v_fmamk_f32 v146, v146, 0x3c800000, v173
	v_mul_f32_e32 v147, 0x4b800000, v146
	v_cmp_gt_f32_e32 vcc, s88, v146
	s_or_b32 s0, s1, s67
	s_lshl_b32 s0, s0, 7
	v_cndmask_b32_e32 v146, v146, v147, vcc
	v_rsq_f32_e32 v146, v146
	v_or3_b32 v178, v201, s0, v157
	v_mul_f32_e32 v179, v92, v92
	v_mul_f32_e32 v147, 0x45800000, v146
	v_cndmask_b32_e32 v194, v146, v147, vcc
	v_pk_mul_f32 v[196:197], v[124:125], v[194:195] op_sel_hi:[1,0]
	v_pk_mul_f32 v[198:199], v[126:127], v[194:195] op_sel_hi:[1,0]
	v_pk_mul_f32 v[200:201], v[120:121], v[194:195] op_sel_hi:[1,0]
	v_pk_mul_f32 v[202:203], v[122:123], v[194:195] op_sel_hi:[1,0]
	v_pk_mul_f32 v[116:117], v[116:117], v[194:195] op_sel_hi:[1,0]
	v_pk_mul_f32 v[108:109], v[108:109], v[194:195] op_sel_hi:[1,0]
	v_pk_mul_f32 v[110:111], v[110:111], v[194:195] op_sel_hi:[1,0]
	v_pk_mul_f32 v[118:119], v[118:119], v[194:195] op_sel_hi:[1,0]
	s_waitcnt vmcnt(0)
	v_pk_mul_f32 v[150:151], v[192:193], v[150:151] op_sel_hi:[0,1]
	v_pk_mul_f32 v[152:153], v[192:193], v[148:149] op_sel_hi:[0,1]
	v_pk_mul_f32 v[146:147], v[192:193], v[182:183] op_sel_hi:[0,1]
	v_pk_mul_f32 v[148:149], v[192:193], v[180:181] op_sel_hi:[0,1]
	v_pk_mul_f32 v[182:183], v[150:151], v[198:199]
	v_pk_mul_f32 v[180:181], v[152:153], v[196:197]
	v_pk_mul_f32 v[124:125], v[192:193], v[186:187] op_sel_hi:[0,1]
	v_pk_mul_f32 v[126:127], v[192:193], v[184:185] op_sel_hi:[0,1]
	v_pk_mul_f32 v[184:185], v[146:147], v[202:203]
	v_pk_mul_f32 v[186:187], v[148:149], v[200:201]
	v_cvt_pk_bf16_f32 v180, v180, v181
	v_cvt_pk_bf16_f32 v181, v182, v183
	v_pk_mul_f32 v[120:121], v[192:193], v[190:191] op_sel_hi:[0,1]
	v_cvt_pk_bf16_f32 v182, v186, v187
	v_cvt_pk_bf16_f32 v183, v184, v185
	buffer_store_dwordx4 v[180:183], v178, s[20:23], 0 offen
	v_pk_mul_f32 v[122:123], v[192:193], v[188:189] op_sel_hi:[0,1]
	v_pk_mul_f32 v[116:117], v[126:127], v[116:117]
	v_pk_mul_f32 v[180:181], v[114:115], v[114:115]
	v_pk_mul_f32 v[182:183], v[112:113], v[112:113]
	v_pk_mul_f32 v[118:119], v[124:125], v[118:119]
	v_pk_mov_b32 v[184:185], v[182:183], v[180:181] op_sel:[1,0]
	v_mov_b32_e32 v183, v181
	v_pk_add_f32 v[180:181], v[184:185], v[182:183]
	v_pk_mul_f32 v[182:183], v[106:107], v[106:107]
	v_pk_mul_f32 v[184:185], v[104:105], v[104:105]
	v_pk_add_f32 v[180:181], v[180:181], v[180:181] op_sel:[0,1] op_sel_hi:[1,0]
	v_pk_mov_b32 v[186:187], v[184:185], v[182:183] op_sel:[1,0]
	v_mov_b32_e32 v185, v183
	v_pk_add_f32 v[182:183], v[186:187], v[184:185]
	v_mul_f32_e32 v184, v93, v93
	v_pk_add_f32 v[182:183], v[182:183], v[182:183] op_sel:[0,1] op_sel_hi:[1,0]
	v_mov_b32_e32 v181, v179
	v_mov_b32_e32 v183, v184
	v_pk_add_f32 v[180:181], v[180:181], v[182:183]
	v_mul_f32_e32 v182, v101, v101
	v_mul_f32_e32 v185, v94, v94
	v_pk_fma_f32 v[182:183], v[100:101], v[100:101], v[182:183] op_sel_hi:[1,1,0]
	v_mul_f32_e32 v184, v103, v103
	v_mul_f32_e32 v186, v95, v95
	v_mov_b32_e32 v183, v185
	v_pk_fma_f32 v[184:185], v[102:103], v[102:103], v[184:185] op_sel_hi:[1,1,0]
	s_nop 0
	v_mov_b32_e32 v185, v186
	v_pk_add_f32 v[182:183], v[182:183], v[184:185]
	s_nop 0
	v_pk_add_f32 v[180:181], v[180:181], v[182:183]
	s_nop 0
	v_add_f32_e32 v179, v180, v181
	ds_bpermute_b32 v180, v136, v179
	s_waitcnt lgkmcnt(0)
; __device__ __forceinline__ unsigned pk2(float lo, float hi) { return pg8::cvt_pk_bf16(lo, hi); }
;     __device__ __forceinline__ void operator()(const f32x4 (&acc)[2][2][4][2], const pg8::Unit& u, int wr, int wc, int fr, int fq) const {
;     ...
;             for (int ai = 0; ai < 2; ++ai)
; #pragma unroll
;                 for (int m = 0; m < 4; ++m) {
;                     float ss = 0.f;
; #pragma unroll
;                     for (int bj = 0; bj < 2; ++bj)
; #pragma unroll
;                         for (int n = 0; n < 2; ++n) { const f32x4 a = acc[ai][bj][m][n]; ss += (a.x * a.x + a.y * a.y) + (a.z * a.z + a.w * a.w); }
;                     ss += __shfl_xor(ss, 16); ss += __shfl_xor(ss, 32);
;                     const float rinv = rsqrtf(ss * (1.f / 64.f) + EPS);
;                     const unsigned row = (unsigned)(row0 + ai * 128 + m * 16);
; #pragma unroll
;                     for (int bj = 0; bj < 2; ++bj) { const f32x4 v0 = acc[ai][bj][m][0] * rinv * gv[bj][0], v1 = acc[ai][bj][m][1] * rinv * gv[bj][1];
;                         u32x4 w; w.x = pk2(v0.x, v0.y); w.y = pk2(v0.z, v0.w); w.z = pk2(v1.x, v1.y); w.w = pk2(v1.z, v1.w);
;                         st16wt(dst, (row * 512 + head * 64 + 32 * bj + 8 * fq) * 2u, w); }
;                 }
	v_add_f32_e32 v179, v179, v180
	ds_bpermute_b32 v182, v177, v179
	v_pk_mul_f32 v[180:181], v[120:121], v[110:111]
	v_pk_mul_f32 v[110:111], v[122:123], v[108:109]
	v_cvt_pk_bf16_f32 v108, v116, v117
	v_cvt_pk_bf16_f32 v109, v118, v119
	s_waitcnt lgkmcnt(0)
	v_add_f32_e32 v116, v179, v182
	v_fmamk_f32 v116, v116, 0x3c800000, v173
	v_mul_f32_e32 v117, 0x4b800000, v116
	v_cmp_gt_f32_e32 vcc, s88, v116
	v_cvt_pk_bf16_f32 v110, v110, v111
	v_cvt_pk_bf16_f32 v111, v180, v181
	buffer_store_dwordx4 v[108:111], v178, s[20:23], 0 offen offset:64
	s_nop 0
	v_cndmask_b32_e32 v116, v116, v117, vcc
	v_rsq_f32_e32 v116, v116
	v_add_u32_e32 v109, 0x4000, v178
	v_mul_f32_e32 v108, 0x45800000, v116
	v_cndmask_b32_e32 v108, v116, v108, vcc
	v_pk_mul_f32 v[104:105], v[104:105], v[108:109] op_sel_hi:[1,0]
	v_pk_mul_f32 v[106:107], v[106:107], v[108:109] op_sel_hi:[1,0]
	v_pk_mul_f32 v[110:111], v[112:113], v[108:109] op_sel_hi:[1,0]
	v_pk_mul_f32 v[112:113], v[114:115], v[108:109] op_sel_hi:[1,0]
	v_pk_mul_f32 v[114:115], v[146:147], v[106:107]
	v_pk_mul_f32 v[106:107], v[148:149], v[104:105]
	v_pk_mul_f32 v[112:113], v[150:151], v[112:113]
	v_pk_mul_f32 v[110:111], v[152:153], v[110:111]
	v_pk_mul_f32 v[100:101], v[100:101], v[108:109] op_sel_hi:[1,0]
	v_cvt_pk_bf16_f32 v104, v110, v111
	v_cvt_pk_bf16_f32 v105, v112, v113
	v_cvt_pk_bf16_f32 v106, v106, v107
	v_cvt_pk_bf16_f32 v107, v114, v115
	buffer_store_dwordx4 v[104:107], v109, s[20:23], 0 offen
	v_pk_mul_f32 v[100:101], v[126:127], v[100:101]
	v_pk_mul_f32 v[92:93], v[92:93], v[108:109] op_sel_hi:[1,0]
	v_pk_mul_f32 v[104:105], v[98:99], v[98:99]
	v_pk_mul_f32 v[106:107], v[96:97], v[96:97]
	v_pk_mul_f32 v[94:95], v[94:95], v[108:109] op_sel_hi:[1,0]
	v_pk_mov_b32 v[110:111], v[106:107], v[104:105] op_sel:[1,0]
	v_mov_b32_e32 v107, v105
	v_pk_add_f32 v[104:105], v[110:111], v[106:107]
	v_pk_mul_f32 v[106:107], v[90:91], v[90:91]
	v_pk_mul_f32 v[110:111], v[88:89], v[88:89]
	v_pk_add_f32 v[104:105], v[104:105], v[104:105] op_sel:[0,1] op_sel_hi:[1,0]
	v_pk_mov_b32 v[112:113], v[110:111], v[106:107] op_sel:[1,0]
	v_mov_b32_e32 v111, v107
	v_pk_add_f32 v[106:107], v[112:113], v[110:111]
	v_mul_f32_e32 v110, v76, v76
	v_mul_f32_e32 v111, v77, v77
	v_pk_add_f32 v[106:107], v[106:107], v[106:107] op_sel:[0,1] op_sel_hi:[1,0]
	v_mov_b32_e32 v105, v110
	v_mov_b32_e32 v107, v111
	v_pk_add_f32 v[104:105], v[104:105], v[106:107]
	v_mul_f32_e32 v106, v85, v85
	v_mul_f32_e32 v110, v87, v87
	v_mul_f32_e32 v112, v78, v78
	v_mul_f32_e32 v113, v79, v79
	v_pk_fma_f32 v[106:107], v[84:85], v[84:85], v[106:107] op_sel_hi:[1,1,0]
	v_pk_fma_f32 v[110:111], v[86:87], v[86:87], v[110:111] op_sel_hi:[1,1,0]
	v_mov_b32_e32 v107, v112
	v_mov_b32_e32 v111, v113
	v_pk_add_f32 v[106:107], v[106:107], v[110:111]
	v_pk_mul_f32 v[102:103], v[102:103], v[108:109] op_sel_hi:[1,0]
	v_pk_add_f32 v[104:105], v[104:105], v[106:107]
	v_pk_mul_f32 v[102:103], v[124:125], v[102:103]
	v_add_f32_e32 v104, v104, v105
	ds_bpermute_b32 v105, v136, v104
	s_waitcnt lgkmcnt(0)
	v_add_f32_e32 v106, v104, v105
	ds_bpermute_b32 v107, v177, v106
	v_pk_mul_f32 v[104:105], v[120:121], v[94:95]
	v_pk_mul_f32 v[94:95], v[122:123], v[92:93]
	v_cvt_pk_bf16_f32 v92, v100, v101
	v_cvt_pk_bf16_f32 v93, v102, v103
	s_waitcnt lgkmcnt(0)
	v_add_f32_e32 v100, v106, v107
	v_fmamk_f32 v100, v100, 0x3c800000, v173
	v_mul_f32_e32 v101, 0x4b800000, v100
	v_cmp_gt_f32_e32 vcc, s88, v100
	v_cvt_pk_bf16_f32 v94, v94, v95
	v_cvt_pk_bf16_f32 v95, v104, v105
	buffer_store_dwordx4 v[92:95], v109, s[20:23], 0 offen offset:64
	s_nop 0
	v_cndmask_b32_e32 v100, v100, v101, vcc
	v_rsq_f32_e32 v100, v100
	v_add_u32_e32 v93, 0x8000, v178
	v_mul_f32_e32 v92, 0x45800000, v100
	v_cndmask_b32_e32 v92, v100, v92, vcc
	v_pk_mul_f32 v[88:89], v[88:89], v[92:93] op_sel_hi:[1,0]
	v_pk_mul_f32 v[90:91], v[90:91], v[92:93] op_sel_hi:[1,0]
	v_pk_mul_f32 v[94:95], v[96:97], v[92:93] op_sel_hi:[1,0]
	v_pk_mul_f32 v[96:97], v[98:99], v[92:93] op_sel_hi:[1,0]
	v_pk_mul_f32 v[98:99], v[146:147], v[90:91]
	v_pk_mul_f32 v[90:91], v[148:149], v[88:89]
	v_pk_mul_f32 v[96:97], v[150:151], v[96:97]
	v_pk_mul_f32 v[94:95], v[152:153], v[94:95]
	v_pk_mul_f32 v[84:85], v[84:85], v[92:93] op_sel_hi:[1,0]
	v_cvt_pk_bf16_f32 v88, v94, v95
	v_cvt_pk_bf16_f32 v89, v96, v97
	v_cvt_pk_bf16_f32 v90, v90, v91
	v_cvt_pk_bf16_f32 v91, v98, v99
	buffer_store_dwordx4 v[88:91], v93, s[20:23], 0 offen
	v_pk_mul_f32 v[84:85], v[126:127], v[84:85]
	v_pk_mul_f32 v[76:77], v[76:77], v[92:93] op_sel_hi:[1,0]
	v_pk_mul_f32 v[88:89], v[82:83], v[82:83]
	v_pk_mul_f32 v[90:91], v[80:81], v[80:81]
	v_pk_mul_f32 v[78:79], v[78:79], v[92:93] op_sel_hi:[1,0]
	v_pk_mov_b32 v[94:95], v[90:91], v[88:89] op_sel:[1,0]
	v_mov_b32_e32 v91, v89
	v_pk_add_f32 v[88:89], v[94:95], v[90:91]
	v_pk_mul_f32 v[90:91], v[74:75], v[74:75]
	v_pk_mul_f32 v[94:95], v[72:73], v[72:73]
	v_pk_add_f32 v[88:89], v[88:89], v[88:89] op_sel:[0,1] op_sel_hi:[1,0]
	v_pk_mov_b32 v[96:97], v[94:95], v[90:91] op_sel:[1,0]
	v_mov_b32_e32 v95, v91
	v_pk_add_f32 v[90:91], v[96:97], v[94:95]
	v_mul_f32_e32 v94, v64, v64
	v_mul_f32_e32 v95, v65, v65
	v_pk_add_f32 v[90:91], v[90:91], v[90:91] op_sel:[0,1] op_sel_hi:[1,0]
	v_mov_b32_e32 v89, v94
	v_mov_b32_e32 v91, v95
	v_pk_add_f32 v[88:89], v[88:89], v[90:91]
	v_mul_f32_e32 v90, v69, v69
	v_mul_f32_e32 v94, v71, v71
	v_mul_f32_e32 v96, v66, v66
	v_mul_f32_e32 v97, v67, v67
	v_pk_fma_f32 v[90:91], v[68:69], v[68:69], v[90:91] op_sel_hi:[1,1,0]
	v_pk_fma_f32 v[94:95], v[70:71], v[70:71], v[94:95] op_sel_hi:[1,1,0]
	v_mov_b32_e32 v91, v96
	v_mov_b32_e32 v95, v97
	v_pk_add_f32 v[90:91], v[90:91], v[94:95]
	v_pk_mul_f32 v[86:87], v[86:87], v[92:93] op_sel_hi:[1,0]
	v_pk_add_f32 v[88:89], v[88:89], v[90:91]
	v_pk_mul_f32 v[86:87], v[124:125], v[86:87]
	v_add_f32_e32 v88, v88, v89
	ds_bpermute_b32 v89, v136, v88
	s_waitcnt lgkmcnt(0)
; __device__ __forceinline__ unsigned pk2(float lo, float hi) { return pg8::cvt_pk_bf16(lo, hi); }
;     __device__ __forceinline__ void operator()(const f32x4 (&acc)[2][2][4][2], const pg8::Unit& u, int wr, int wc, int fr, int fq) const {
;     ...
;             for (int ai = 0; ai < 2; ++ai)
; #pragma unroll
;                 for (int m = 0; m < 4; ++m) {
;                     float ss = 0.f;
; #pragma unroll
;                     for (int bj = 0; bj < 2; ++bj)
; #pragma unroll
;                         for (int n = 0; n < 2; ++n) { const f32x4 a = acc[ai][bj][m][n]; ss += (a.x * a.x + a.y * a.y) + (a.z * a.z + a.w * a.w); }
;                     ss += __shfl_xor(ss, 16); ss += __shfl_xor(ss, 32);
;                     const float rinv = rsqrtf(ss * (1.f / 64.f) + EPS);
;                     const unsigned row = (unsigned)(row0 + ai * 128 + m * 16);
; #pragma unroll
;                     for (int bj = 0; bj < 2; ++bj) { const f32x4 v0 = acc[ai][bj][m][0] * rinv * gv[bj][0], v1 = acc[ai][bj][m][1] * rinv * gv[bj][1];
;                         u32x4 w; w.x = pk2(v0.x, v0.y); w.y = pk2(v0.z, v0.w); w.z = pk2(v1.x, v1.y); w.w = pk2(v1.z, v1.w);
;                         st16wt(dst, (row * 512 + head * 64 + 32 * bj + 8 * fq) * 2u, w); }
;                 }
	v_add_f32_e32 v90, v88, v89
	ds_bpermute_b32 v91, v177, v90
	v_pk_mul_f32 v[88:89], v[120:121], v[78:79]
	v_pk_mul_f32 v[78:79], v[122:123], v[76:77]
	v_cvt_pk_bf16_f32 v76, v84, v85
	v_cvt_pk_bf16_f32 v77, v86, v87
	s_waitcnt lgkmcnt(0)
	v_add_f32_e32 v84, v90, v91
	v_fmamk_f32 v84, v84, 0x3c800000, v173
	v_mul_f32_e32 v85, 0x4b800000, v84
	v_cmp_gt_f32_e32 vcc, s88, v84
	v_cvt_pk_bf16_f32 v78, v78, v79
	v_cvt_pk_bf16_f32 v79, v88, v89
	buffer_store_dwordx4 v[76:79], v93, s[20:23], 0 offen offset:64
	s_nop 0
	v_cndmask_b32_e32 v84, v84, v85, vcc
	v_rsq_f32_e32 v84, v84
	v_add_u32_e32 v77, 0xc000, v178
	v_mul_f32_e32 v76, 0x45800000, v84
	v_cndmask_b32_e32 v76, v84, v76, vcc
	v_pk_mul_f32 v[72:73], v[72:73], v[76:77] op_sel_hi:[1,0]
	v_pk_mul_f32 v[74:75], v[74:75], v[76:77] op_sel_hi:[1,0]
	v_pk_mul_f32 v[78:79], v[80:81], v[76:77] op_sel_hi:[1,0]
	v_pk_mul_f32 v[80:81], v[82:83], v[76:77] op_sel_hi:[1,0]
	v_pk_mul_f32 v[82:83], v[146:147], v[74:75]
	v_pk_mul_f32 v[74:75], v[148:149], v[72:73]
	v_pk_mul_f32 v[80:81], v[150:151], v[80:81]
	v_pk_mul_f32 v[78:79], v[152:153], v[78:79]
	v_pk_mul_f32 v[64:65], v[64:65], v[76:77] op_sel_hi:[1,0]
	v_cvt_pk_bf16_f32 v72, v78, v79
	v_cvt_pk_bf16_f32 v73, v80, v81
	v_cvt_pk_bf16_f32 v74, v74, v75
	v_cvt_pk_bf16_f32 v75, v82, v83
	buffer_store_dwordx4 v[72:75], v77, s[20:23], 0 offen
	v_pk_mul_f32 v[66:67], v[66:67], v[76:77] op_sel_hi:[1,0]
	v_pk_mul_f32 v[68:69], v[68:69], v[76:77] op_sel_hi:[1,0]
	v_pk_mul_f32 v[72:73], v[62:63], v[62:63]
	v_pk_mul_f32 v[74:75], v[60:61], v[60:61]
	v_pk_mul_f32 v[70:71], v[70:71], v[76:77] op_sel_hi:[1,0]
	v_pk_mov_b32 v[78:79], v[74:75], v[72:73] op_sel:[1,0]
	v_mov_b32_e32 v75, v73
	v_pk_add_f32 v[72:73], v[78:79], v[74:75]
	v_pk_mul_f32 v[74:75], v[58:59], v[58:59]
	v_pk_mul_f32 v[78:79], v[56:57], v[56:57]
	v_pk_add_f32 v[72:73], v[72:73], v[72:73] op_sel:[0,1] op_sel_hi:[1,0]
	v_pk_mov_b32 v[80:81], v[78:79], v[74:75] op_sel:[1,0]
	v_mov_b32_e32 v79, v75
	v_pk_add_f32 v[74:75], v[80:81], v[78:79]
	v_mul_f32_e32 v78, v44, v44
	v_mul_f32_e32 v79, v45, v45
	v_pk_add_f32 v[74:75], v[74:75], v[74:75] op_sel:[0,1] op_sel_hi:[1,0]
	v_mov_b32_e32 v73, v78
	v_mov_b32_e32 v75, v79
	v_pk_add_f32 v[72:73], v[72:73], v[74:75]
	v_mul_f32_e32 v74, v53, v53
	v_mul_f32_e32 v78, v55, v55
	v_mul_f32_e32 v80, v46, v46
	v_mul_f32_e32 v81, v47, v47
	v_pk_fma_f32 v[74:75], v[52:53], v[52:53], v[74:75] op_sel_hi:[1,1,0]
	v_pk_fma_f32 v[78:79], v[54:55], v[54:55], v[78:79] op_sel_hi:[1,1,0]
	v_mov_b32_e32 v75, v80
	v_mov_b32_e32 v79, v81
	v_pk_add_f32 v[74:75], v[74:75], v[78:79]
	v_pk_mul_f32 v[70:71], v[124:125], v[70:71]
	v_pk_add_f32 v[72:73], v[72:73], v[74:75]
	v_pk_mul_f32 v[68:69], v[126:127], v[68:69]
	v_add_f32_e32 v74, v72, v73
	ds_bpermute_b32 v75, v136, v74
	v_pk_mul_f32 v[72:73], v[120:121], v[66:67]
	v_pk_mul_f32 v[66:67], v[122:123], v[64:65]
	v_cvt_pk_bf16_f32 v64, v68, v69
	v_cvt_pk_bf16_f32 v65, v70, v71
	s_waitcnt lgkmcnt(0)
	v_add_f32_e32 v74, v74, v75
	ds_bpermute_b32 v75, v177, v74
	v_cvt_pk_bf16_f32 v66, v66, v67
	s_waitcnt lgkmcnt(0)
	v_add_f32_e32 v67, v74, v75
	v_fmamk_f32 v67, v67, 0x3c800000, v173
	v_mul_f32_e32 v68, 0x4b800000, v67
	v_cmp_gt_f32_e32 vcc, s88, v67
	s_nop 1
	v_cndmask_b32_e32 v67, v67, v68, vcc
	v_rsq_f32_e32 v68, v67
	v_cvt_pk_bf16_f32 v67, v72, v73
	buffer_store_dwordx4 v[64:67], v77, s[20:23], 0 offen offset:64
	s_nop 1
	v_mul_f32_e32 v64, 0x45800000, v68
	v_add_u32_e32 v65, 0x20000, v178
	v_cndmask_b32_e32 v64, v68, v64, vcc
	v_pk_mul_f32 v[56:57], v[56:57], v[64:65] op_sel_hi:[1,0]
	v_pk_mul_f32 v[58:59], v[58:59], v[64:65] op_sel_hi:[1,0]
	v_pk_mul_f32 v[60:61], v[60:61], v[64:65] op_sel_hi:[1,0]
	v_pk_mul_f32 v[62:63], v[62:63], v[64:65] op_sel_hi:[1,0]
	v_pk_mul_f32 v[66:67], v[146:147], v[58:59]
	v_pk_mul_f32 v[58:59], v[148:149], v[56:57]
	v_pk_mul_f32 v[62:63], v[150:151], v[62:63]
	v_pk_mul_f32 v[60:61], v[152:153], v[60:61]
	v_pk_mul_f32 v[52:53], v[52:53], v[64:65] op_sel_hi:[1,0]
	v_cvt_pk_bf16_f32 v56, v60, v61
	v_cvt_pk_bf16_f32 v57, v62, v63
	v_cvt_pk_bf16_f32 v58, v58, v59
	v_cvt_pk_bf16_f32 v59, v66, v67
	buffer_store_dwordx4 v[56:59], v65, s[20:23], 0 offen
	v_pk_mul_f32 v[52:53], v[126:127], v[52:53]
	v_pk_mul_f32 v[44:45], v[44:45], v[64:65] op_sel_hi:[1,0]
	v_pk_mul_f32 v[56:57], v[50:51], v[50:51]
	v_pk_mul_f32 v[58:59], v[48:49], v[48:49]
	v_pk_mul_f32 v[46:47], v[46:47], v[64:65] op_sel_hi:[1,0]
	v_pk_mov_b32 v[60:61], v[58:59], v[56:57] op_sel:[1,0]
	v_mov_b32_e32 v59, v57
	v_pk_add_f32 v[56:57], v[60:61], v[58:59]
	v_pk_mul_f32 v[58:59], v[42:43], v[42:43]
	v_pk_mul_f32 v[60:61], v[40:41], v[40:41]
	v_pk_add_f32 v[56:57], v[56:57], v[56:57] op_sel:[0,1] op_sel_hi:[1,0]
	v_pk_mov_b32 v[62:63], v[60:61], v[58:59] op_sel:[1,0]
	v_mov_b32_e32 v61, v59
	v_pk_add_f32 v[58:59], v[62:63], v[60:61]
	v_mul_f32_e32 v60, v28, v28
	v_mul_f32_e32 v61, v29, v29
	v_pk_add_f32 v[58:59], v[58:59], v[58:59] op_sel:[0,1] op_sel_hi:[1,0]
	v_mov_b32_e32 v57, v60
	v_mov_b32_e32 v59, v61
	v_pk_add_f32 v[56:57], v[56:57], v[58:59]
	v_mul_f32_e32 v58, v37, v37
	v_mul_f32_e32 v60, v39, v39
	v_mul_f32_e32 v62, v30, v30
	v_mul_f32_e32 v63, v31, v31
	v_pk_fma_f32 v[58:59], v[36:37], v[36:37], v[58:59] op_sel_hi:[1,1,0]
	v_pk_fma_f32 v[60:61], v[38:39], v[38:39], v[60:61] op_sel_hi:[1,1,0]
	v_mov_b32_e32 v59, v62
	v_mov_b32_e32 v61, v63
	v_pk_add_f32 v[58:59], v[58:59], v[60:61]
	v_pk_mul_f32 v[54:55], v[54:55], v[64:65] op_sel_hi:[1,0]
	v_pk_add_f32 v[56:57], v[56:57], v[58:59]
	v_pk_mul_f32 v[54:55], v[124:125], v[54:55]
	v_add_f32_e32 v56, v56, v57
	ds_bpermute_b32 v57, v136, v56
	s_waitcnt lgkmcnt(0)
; __device__ __forceinline__ unsigned pk2(float lo, float hi) { return pg8::cvt_pk_bf16(lo, hi); }
;     __device__ __forceinline__ void operator()(const f32x4 (&acc)[2][2][4][2], const pg8::Unit& u, int wr, int wc, int fr, int fq) const {
;     ...
;             for (int ai = 0; ai < 2; ++ai)
; #pragma unroll
;                 for (int m = 0; m < 4; ++m) {
;                     float ss = 0.f;
; #pragma unroll
;                     for (int bj = 0; bj < 2; ++bj)
; #pragma unroll
;                         for (int n = 0; n < 2; ++n) { const f32x4 a = acc[ai][bj][m][n]; ss += (a.x * a.x + a.y * a.y) + (a.z * a.z + a.w * a.w); }
;                     ss += __shfl_xor(ss, 16); ss += __shfl_xor(ss, 32);
;                     const float rinv = rsqrtf(ss * (1.f / 64.f) + EPS);
;                     const unsigned row = (unsigned)(row0 + ai * 128 + m * 16);
; #pragma unroll
;                     for (int bj = 0; bj < 2; ++bj) { const f32x4 v0 = acc[ai][bj][m][0] * rinv * gv[bj][0], v1 = acc[ai][bj][m][1] * rinv * gv[bj][1];
;                         u32x4 w; w.x = pk2(v0.x, v0.y); w.y = pk2(v0.z, v0.w); w.z = pk2(v1.x, v1.y); w.w = pk2(v1.z, v1.w);
;                         st16wt(dst, (row * 512 + head * 64 + 32 * bj + 8 * fq) * 2u, w); }
;                 }
	v_add_f32_e32 v58, v56, v57
	ds_bpermute_b32 v59, v177, v58
	v_pk_mul_f32 v[56:57], v[120:121], v[46:47]
	v_pk_mul_f32 v[46:47], v[122:123], v[44:45]
	v_cvt_pk_bf16_f32 v44, v52, v53
	v_cvt_pk_bf16_f32 v45, v54, v55
	s_waitcnt lgkmcnt(0)
	v_add_f32_e32 v52, v58, v59
	v_fmamk_f32 v52, v52, 0x3c800000, v173
	v_mul_f32_e32 v53, 0x4b800000, v52
	v_cmp_gt_f32_e32 vcc, s88, v52
	v_cvt_pk_bf16_f32 v46, v46, v47
	v_cvt_pk_bf16_f32 v47, v56, v57
	buffer_store_dwordx4 v[44:47], v65, s[20:23], 0 offen offset:64
	s_nop 0
	v_cndmask_b32_e32 v52, v52, v53, vcc
	v_rsq_f32_e32 v52, v52
	v_add_u32_e32 v45, 0x24000, v178
	v_mul_f32_e32 v44, 0x45800000, v52
	v_cndmask_b32_e32 v44, v52, v44, vcc
	v_pk_mul_f32 v[40:41], v[40:41], v[44:45] op_sel_hi:[1,0]
	v_pk_mul_f32 v[42:43], v[42:43], v[44:45] op_sel_hi:[1,0]
	v_pk_mul_f32 v[46:47], v[48:49], v[44:45] op_sel_hi:[1,0]
	v_pk_mul_f32 v[48:49], v[50:51], v[44:45] op_sel_hi:[1,0]
	v_pk_mul_f32 v[50:51], v[146:147], v[42:43]
	v_pk_mul_f32 v[42:43], v[148:149], v[40:41]
	v_pk_mul_f32 v[48:49], v[150:151], v[48:49]
	v_pk_mul_f32 v[46:47], v[152:153], v[46:47]
	v_pk_mul_f32 v[36:37], v[36:37], v[44:45] op_sel_hi:[1,0]
	v_cvt_pk_bf16_f32 v40, v46, v47
	v_cvt_pk_bf16_f32 v41, v48, v49
	v_cvt_pk_bf16_f32 v42, v42, v43
	v_cvt_pk_bf16_f32 v43, v50, v51
	buffer_store_dwordx4 v[40:43], v45, s[20:23], 0 offen
	v_pk_mul_f32 v[36:37], v[126:127], v[36:37]
	v_pk_mul_f32 v[28:29], v[28:29], v[44:45] op_sel_hi:[1,0]
	v_pk_mul_f32 v[40:41], v[34:35], v[34:35]
	v_pk_mul_f32 v[42:43], v[32:33], v[32:33]
	v_pk_mul_f32 v[30:31], v[30:31], v[44:45] op_sel_hi:[1,0]
	v_pk_mov_b32 v[46:47], v[42:43], v[40:41] op_sel:[1,0]
	v_mov_b32_e32 v43, v41
	v_pk_add_f32 v[40:41], v[46:47], v[42:43]
	v_pk_mul_f32 v[42:43], v[26:27], v[26:27]
	v_pk_mul_f32 v[46:47], v[24:25], v[24:25]
	v_pk_add_f32 v[40:41], v[40:41], v[40:41] op_sel:[0,1] op_sel_hi:[1,0]
	v_pk_mov_b32 v[48:49], v[46:47], v[42:43] op_sel:[1,0]
	v_mov_b32_e32 v47, v43
	v_pk_add_f32 v[42:43], v[48:49], v[46:47]
	v_mul_f32_e32 v46, v12, v12
	v_mul_f32_e32 v47, v13, v13
	v_pk_add_f32 v[42:43], v[42:43], v[42:43] op_sel:[0,1] op_sel_hi:[1,0]
	v_mov_b32_e32 v41, v46
	v_mov_b32_e32 v43, v47
	v_pk_add_f32 v[40:41], v[40:41], v[42:43]
	v_mul_f32_e32 v42, v21, v21
	v_mul_f32_e32 v46, v23, v23
	v_mul_f32_e32 v48, v14, v14
	v_mul_f32_e32 v49, v15, v15
	v_pk_fma_f32 v[42:43], v[20:21], v[20:21], v[42:43] op_sel_hi:[1,1,0]
	v_pk_fma_f32 v[46:47], v[22:23], v[22:23], v[46:47] op_sel_hi:[1,1,0]
	v_mov_b32_e32 v43, v48
	v_mov_b32_e32 v47, v49
	v_pk_add_f32 v[42:43], v[42:43], v[46:47]
	v_pk_mul_f32 v[38:39], v[38:39], v[44:45] op_sel_hi:[1,0]
	v_pk_add_f32 v[40:41], v[40:41], v[42:43]
	v_pk_mul_f32 v[38:39], v[124:125], v[38:39]
	v_add_f32_e32 v40, v40, v41
	ds_bpermute_b32 v41, v136, v40
	s_waitcnt lgkmcnt(0)
	v_add_f32_e32 v42, v40, v41
	ds_bpermute_b32 v43, v177, v42
	v_pk_mul_f32 v[40:41], v[120:121], v[30:31]
	v_pk_mul_f32 v[30:31], v[122:123], v[28:29]
	v_cvt_pk_bf16_f32 v28, v36, v37
	v_cvt_pk_bf16_f32 v29, v38, v39
	s_waitcnt lgkmcnt(0)
; __device__ __forceinline__ unsigned pk2(float lo, float hi) { return pg8::cvt_pk_bf16(lo, hi); }
;     __device__ __forceinline__ void operator()(const f32x4 (&acc)[2][2][4][2], const pg8::Unit& u, int wr, int wc, int fr, int fq) const {
;     ...
;             for (int ai = 0; ai < 2; ++ai)
; #pragma unroll
;                 for (int m = 0; m < 4; ++m) {
;                     float ss = 0.f;
; #pragma unroll
;                     for (int bj = 0; bj < 2; ++bj)
; #pragma unroll
;                         for (int n = 0; n < 2; ++n) { const f32x4 a = acc[ai][bj][m][n]; ss += (a.x * a.x + a.y * a.y) + (a.z * a.z + a.w * a.w); }
;                     ss += __shfl_xor(ss, 16); ss += __shfl_xor(ss, 32);
;                     const float rinv = rsqrtf(ss * (1.f / 64.f) + EPS);
;                     const unsigned row = (unsigned)(row0 + ai * 128 + m * 16);
; #pragma unroll
;                     for (int bj = 0; bj < 2; ++bj) { const f32x4 v0 = acc[ai][bj][m][0] * rinv * gv[bj][0], v1 = acc[ai][bj][m][1] * rinv * gv[bj][1];
;                         u32x4 w; w.x = pk2(v0.x, v0.y); w.y = pk2(v0.z, v0.w); w.z = pk2(v1.x, v1.y); w.w = pk2(v1.z, v1.w);
;                         st16wt(dst, (row * 512 + head * 64 + 32 * bj + 8 * fq) * 2u, w); }
;                 }
	v_add_f32_e32 v36, v42, v43
	v_fmamk_f32 v36, v36, 0x3c800000, v173
	v_mul_f32_e32 v37, 0x4b800000, v36
	v_cmp_gt_f32_e32 vcc, s88, v36
	v_cvt_pk_bf16_f32 v30, v30, v31
	v_cvt_pk_bf16_f32 v31, v40, v41
	buffer_store_dwordx4 v[28:31], v45, s[20:23], 0 offen offset:64
	s_nop 0
	v_cndmask_b32_e32 v36, v36, v37, vcc
	v_rsq_f32_e32 v36, v36
	v_add_u32_e32 v29, 0x28000, v178
	v_mul_f32_e32 v28, 0x45800000, v36
	v_cndmask_b32_e32 v28, v36, v28, vcc
	v_pk_mul_f32 v[24:25], v[24:25], v[28:29] op_sel_hi:[1,0]
	v_pk_mul_f32 v[26:27], v[26:27], v[28:29] op_sel_hi:[1,0]
	v_pk_mul_f32 v[30:31], v[32:33], v[28:29] op_sel_hi:[1,0]
	v_pk_mul_f32 v[32:33], v[34:35], v[28:29] op_sel_hi:[1,0]
	v_pk_mul_f32 v[34:35], v[146:147], v[26:27]
	v_pk_mul_f32 v[26:27], v[148:149], v[24:25]
	v_pk_mul_f32 v[32:33], v[150:151], v[32:33]
	v_pk_mul_f32 v[30:31], v[152:153], v[30:31]
	v_pk_mul_f32 v[20:21], v[20:21], v[28:29] op_sel_hi:[1,0]
	v_cvt_pk_bf16_f32 v24, v30, v31
	v_cvt_pk_bf16_f32 v25, v32, v33
	v_cvt_pk_bf16_f32 v26, v26, v27
	v_cvt_pk_bf16_f32 v27, v34, v35
	buffer_store_dwordx4 v[24:27], v29, s[20:23], 0 offen
	v_pk_mul_f32 v[20:21], v[126:127], v[20:21]
	v_pk_mul_f32 v[12:13], v[12:13], v[28:29] op_sel_hi:[1,0]
	v_pk_mul_f32 v[24:25], v[18:19], v[18:19]
	v_pk_mul_f32 v[26:27], v[16:17], v[16:17]
	v_pk_mul_f32 v[14:15], v[14:15], v[28:29] op_sel_hi:[1,0]
	v_pk_mov_b32 v[30:31], v[26:27], v[24:25] op_sel:[1,0]
	v_mov_b32_e32 v27, v25
	v_pk_add_f32 v[24:25], v[30:31], v[26:27]
	v_pk_mul_f32 v[26:27], v[10:11], v[10:11]
	v_pk_mul_f32 v[30:31], v[8:9], v[8:9]
	v_pk_add_f32 v[24:25], v[24:25], v[24:25] op_sel:[0,1] op_sel_hi:[1,0]
	v_pk_mov_b32 v[32:33], v[30:31], v[26:27] op_sel:[1,0]
	v_mov_b32_e32 v31, v27
	v_pk_add_f32 v[26:27], v[32:33], v[30:31]
	v_mul_f32_e32 v30, v0, v0
	v_mul_f32_e32 v31, v1, v1
	v_pk_add_f32 v[26:27], v[26:27], v[26:27] op_sel:[0,1] op_sel_hi:[1,0]
	v_mov_b32_e32 v25, v30
	v_mov_b32_e32 v27, v31
	v_pk_add_f32 v[24:25], v[24:25], v[26:27]
	v_mul_f32_e32 v26, v5, v5
	v_mul_f32_e32 v30, v7, v7
	v_mul_f32_e32 v32, v2, v2
	v_mul_f32_e32 v33, v3, v3
	v_pk_fma_f32 v[26:27], v[4:5], v[4:5], v[26:27] op_sel_hi:[1,1,0]
	v_pk_fma_f32 v[30:31], v[6:7], v[6:7], v[30:31] op_sel_hi:[1,1,0]
	v_mov_b32_e32 v27, v32
	v_mov_b32_e32 v31, v33
	v_pk_add_f32 v[26:27], v[26:27], v[30:31]
	v_pk_mul_f32 v[22:23], v[22:23], v[28:29] op_sel_hi:[1,0]
	v_pk_add_f32 v[24:25], v[24:25], v[26:27]
	v_pk_mul_f32 v[22:23], v[124:125], v[22:23]
	v_add_f32_e32 v24, v24, v25
	ds_bpermute_b32 v25, v136, v24
	s_waitcnt lgkmcnt(0)
	v_add_f32_e32 v26, v24, v25
	ds_bpermute_b32 v27, v177, v26
	v_pk_mul_f32 v[24:25], v[120:121], v[14:15]
	v_pk_mul_f32 v[14:15], v[122:123], v[12:13]
	v_cvt_pk_bf16_f32 v12, v20, v21
	v_cvt_pk_bf16_f32 v13, v22, v23
	s_waitcnt lgkmcnt(0)
	v_add_f32_e32 v20, v26, v27
	v_fmamk_f32 v20, v20, 0x3c800000, v173
	v_mul_f32_e32 v21, 0x4b800000, v20
	v_cmp_gt_f32_e32 vcc, s88, v20
	v_cvt_pk_bf16_f32 v14, v14, v15
	v_cvt_pk_bf16_f32 v15, v24, v25
	buffer_store_dwordx4 v[12:15], v29, s[20:23], 0 offen offset:64
	s_nop 0
	v_cndmask_b32_e32 v20, v20, v21, vcc
	v_rsq_f32_e32 v20, v20
	v_add_u32_e32 v13, 0x2c000, v178
	v_mul_f32_e32 v12, 0x45800000, v20
	v_cndmask_b32_e32 v12, v20, v12, vcc
	v_pk_mul_f32 v[14:15], v[16:17], v[12:13] op_sel_hi:[1,0]
	v_pk_mul_f32 v[16:17], v[18:19], v[12:13] op_sel_hi:[1,0]
	v_pk_mul_f32 v[8:9], v[8:9], v[12:13] op_sel_hi:[1,0]
	v_pk_mul_f32 v[10:11], v[10:11], v[12:13] op_sel_hi:[1,0]
	v_pk_mul_f32 v[16:17], v[150:151], v[16:17]
	v_pk_mul_f32 v[14:15], v[152:153], v[14:15]
	v_pk_mul_f32 v[18:19], v[146:147], v[10:11]
	v_pk_mul_f32 v[10:11], v[148:149], v[8:9]
	v_cvt_pk_bf16_f32 v8, v14, v15
	v_cvt_pk_bf16_f32 v9, v16, v17
	v_pk_mul_f32 v[0:1], v[0:1], v[12:13] op_sel_hi:[1,0]
	v_pk_mul_f32 v[2:3], v[2:3], v[12:13] op_sel_hi:[1,0]
	v_cvt_pk_bf16_f32 v10, v10, v11
	v_cvt_pk_bf16_f32 v11, v18, v19
	buffer_store_dwordx4 v[8:11], v13, s[20:23], 0 offen
	v_pk_mul_f32 v[4:5], v[4:5], v[12:13] op_sel_hi:[1,0]
	v_pk_mul_f32 v[6:7], v[6:7], v[12:13] op_sel_hi:[1,0]
	v_pk_mul_f32 v[8:9], v[120:121], v[2:3]
	v_pk_mul_f32 v[2:3], v[122:123], v[0:1]
	v_pk_mul_f32 v[6:7], v[124:125], v[6:7]
	v_pk_mul_f32 v[4:5], v[126:127], v[4:5]
	s_nop 0
	v_cvt_pk_bf16_f32 v0, v4, v5
	v_cvt_pk_bf16_f32 v1, v6, v7
	v_cvt_pk_bf16_f32 v2, v2, v3
	v_cvt_pk_bf16_f32 v3, v8, v9
	buffer_store_dwordx4 v[0:3], v13, s[20:23], 0 offen offset:64
	s_andn2_b64 vcc, exec, s[8:9]
	s_mov_b64 s[8:9], -1
	s_cbranch_vccnz .LBB0_270
